# v070 + each MFMA group of the attention step leads with two back-to-back MFMAs (scalar address math, prefetch loads and the exp pre-fill moved behind them)
# baseline (speedup 1.0000x reference)
.Lattn_fx_top:
	s_waitcnt lgkmcnt(0)
	v_mfma_f32_32x32x16_bf16 v[114:129], v[162:165], v[130:133], v[50:65]
	v_mfma_f32_32x32x16_bf16 v[98:113], v[178:181], v[130:133], v[50:65]
	s_add_i32 s11, s10, -1
	s_min_i32 s1, s11, s58
	s_mul_i32 s44, s1, 0xa0000
	s_add_u32 s44, s3, s44
	s_addc_u32 s45, s12, 0
	s_lshl_b32 s46, s1, 7
	s_add_u32 s46, s15, s46
	s_addc_u32 s47, s23, 0
	s_add_i32 s24, s10, -2
	s_cmp_lt_u32 s24, s16
	s_cselect_b64 s[0:1], -1, 0
	global_load_dwordx4 v[154:157], v252, s[44:45] offset:1024
	global_load_dwordx4 v[158:161], v253, s[46:47]
	v_exp_f32_e32 v66, v66
	v_exp_f32_e32 v67, v67
	v_exp_f32_e32 v68, v68
	v_exp_f32_e32 v69, v69
	v_add_f32_e32 v246, v66, v67
	v_cvt_pk_bf16_f32 v66, v66, v67
	ds_read_b128 v[86:89], v248 offset:36864
	ds_read_b128 v[216:219], v248 offset:41472
	v_exp_f32_e32 v70, v70
	v_exp_f32_e32 v71, v71
	v_add_f32_e32 v246, v68, v246
	v_add_f32_e32 v246, v69, v246
	v_cvt_pk_bf16_f32 v67, v68, v69
	ds_read_b128 v[90:93], v248 offset:36896
	ds_read_b128 v[220:223], v248 offset:41504
	v_exp_f32_e32 v72, v72
	v_exp_f32_e32 v73, v73
	v_add_f32_e32 v246, v70, v246
	v_add_f32_e32 v246, v71, v246
	v_cvt_pk_bf16_f32 v68, v70, v71
	v_mfma_f32_32x32x16_bf16 v[114:129], v[166:169], v[134:137], v[114:129]
	ds_read_b128 v[94:97], v248 offset:36928
	ds_read_b128 v[224:227], v248 offset:41536
	v_exp_f32_e32 v74, v74
	v_exp_f32_e32 v75, v75
	v_add_f32_e32 v246, v72, v246
	v_add_f32_e32 v246, v73, v246
	v_cvt_pk_bf16_f32 v69, v72, v73
	v_mfma_f32_32x32x16_bf16 v[98:113], v[182:185], v[134:137], v[98:113]
	ds_read_b128 v[212:215], v248 offset:36960
	ds_read_b128 v[242:245], v248 offset:41568
	v_exp_f32_e32 v76, v76
	v_exp_f32_e32 v77, v77
	v_add_f32_e32 v246, v74, v246
	v_add_f32_e32 v246, v75, v246
	v_cvt_pk_bf16_f32 v70, v74, v75
	v_mfma_f32_32x32x16_bf16 v[114:129], v[170:173], v[138:141], v[114:129]
	s_cmp_ge_u32 s24, s16
	s_cbranch_scc1 .Lattn_fx_skipw1
	s_waitcnt vmcnt(2)
	ds_write_b128 v192, v[146:149] offset:18432
	ds_write_b128 v204, v[150:153] offset:27648
.Lattn_fx_skipw1:
	v_exp_f32_e32 v78, v78
	v_exp_f32_e32 v79, v79
	v_add_f32_e32 v246, v76, v246
	v_add_f32_e32 v246, v77, v246
	v_cvt_pk_bf16_f32 v71, v76, v77
	v_mfma_f32_32x32x16_bf16 v[98:113], v[186:189], v[138:141], v[98:113]
	v_exp_f32_e32 v80, v80
	v_exp_f32_e32 v81, v81
	v_add_f32_e32 v246, v78, v246
	v_add_f32_e32 v246, v79, v246
	v_cvt_pk_bf16_f32 v72, v78, v79
	v_mfma_f32_32x32x16_bf16 v[114:129], v[174:177], v[142:145], v[114:129]
	v_exp_f32_e32 v34, v34
	v_exp_f32_e32 v35, v35
	v_add_f32_e32 v246, v80, v246
	v_add_f32_e32 v246, v81, v246
	v_cvt_pk_bf16_f32 v73, v80, v81
	v_mfma_f32_32x32x16_bf16 v[98:113], v[82:85], v[142:145], v[98:113]
	v_exp_f32_e32 v36, v36
	v_exp_f32_e32 v37, v37
	v_add_f32_e32 v247, v34, v35
	v_cvt_pk_bf16_f32 v74, v34, v35
	s_waitcnt lgkmcnt(0)
	s_barrier
	v_mfma_f32_32x32x16_bf16 v[18:33], v[86:89], v[66:69], v[18:33]
	v_mfma_f32_32x32x16_bf16 v[2:17], v[216:219], v[66:69], v[2:17]
	ds_read_b128 v[162:165], v193 offset:18432
	ds_read_b128 v[178:181], v193 offset:23040
	v_exp_f32_e32 v38, v38
	v_exp_f32_e32 v39, v39
	v_add_f32_e32 v247, v36, v247
	v_add_f32_e32 v247, v37, v247
	v_cvt_pk_bf16_f32 v75, v36, v37
	ds_read_b128 v[166:169], v193 offset:18464
	ds_read_b128 v[182:185], v193 offset:23072
	v_exp_f32_e32 v40, v40
	v_exp_f32_e32 v41, v41
	v_add_f32_e32 v247, v38, v247
	v_add_f32_e32 v247, v39, v247
	v_cvt_pk_bf16_f32 v76, v38, v39
	v_mfma_f32_32x32x16_bf16 v[18:33], v[90:93], v[70:73], v[18:33]
	ds_read_b128 v[170:173], v193 offset:18496
	ds_read_b128 v[186:189], v193 offset:23104
	v_exp_f32_e32 v42, v42
	v_exp_f32_e32 v43, v43
	v_add_f32_e32 v247, v40, v247
	v_add_f32_e32 v247, v41, v247
	v_cvt_pk_bf16_f32 v77, v40, v41
	v_mfma_f32_32x32x16_bf16 v[2:17], v[220:223], v[70:73], v[2:17]
	ds_read_b128 v[174:177], v193 offset:18528
	ds_read_b128 v[82:85], v193 offset:23136
	v_exp_f32_e32 v44, v44
	v_exp_f32_e32 v45, v45
	v_add_f32_e32 v247, v42, v247
	v_add_f32_e32 v247, v43, v247
	v_cvt_pk_bf16_f32 v78, v42, v43
	v_mfma_f32_32x32x16_bf16 v[18:33], v[94:97], v[74:77], v[18:33]
	v_exp_f32_e32 v46, v46
	v_exp_f32_e32 v47, v47
	v_add_f32_e32 v247, v44, v247
	v_add_f32_e32 v247, v45, v247
	v_cvt_pk_bf16_f32 v79, v44, v45
	v_mfma_f32_32x32x16_bf16 v[2:17], v[224:227], v[74:77], v[2:17]
	v_exp_f32_e32 v48, v48
	v_exp_f32_e32 v49, v49
	v_add_f32_e32 v247, v46, v247
	v_add_f32_e32 v247, v47, v247
	v_cvt_pk_bf16_f32 v80, v46, v47
	v_cvt_pk_bf16_f32 v81, v48, v49
	v_add_f32_e32 v247, v48, v247
	v_add_f32_e32 v247, v49, v247
	v_mfma_f32_32x32x16_bf16 v[18:33], v[212:215], v[78:81], v[18:33]
	v_mfma_f32_32x32x16_bf16 v[2:17], v[242:245], v[78:81], v[2:17]
	v_add_f32_e32 v210, v210, v246
	v_add_f32_e32 v210, v210, v247
	s_waitcnt lgkmcnt(0)
	v_mfma_f32_32x32x16_bf16 v[66:81], v[162:165], v[130:133], v[50:65]
	v_mfma_f32_32x32x16_bf16 v[34:49], v[178:181], v[130:133], v[50:65]
	s_min_i32 s24, s10, s58
	s_mul_i32 s44, s24, 0xa0000
	s_add_u32 s44, s3, s44
	s_addc_u32 s45, s12, 0
	s_lshl_b32 s46, s24, 7
	s_add_u32 s46, s15, s46
	s_addc_u32 s47, s23, 0
	global_load_dwordx4 v[146:149], v252, s[44:45] offset:1024
	global_load_dwordx4 v[150:153], v253, s[46:47]
	v_exp_f32_e32 v114, v114
	v_exp_f32_e32 v115, v115
	v_exp_f32_e32 v116, v116
	v_exp_f32_e32 v117, v117
	v_add_f32_e32 v246, v114, v115
	v_cvt_pk_bf16_f32 v114, v114, v115
	ds_read_b128 v[86:89], v248
	ds_read_b128 v[216:219], v248 offset:4608
	v_exp_f32_e32 v118, v118
	v_exp_f32_e32 v119, v119
	v_add_f32_e32 v246, v116, v246
	v_add_f32_e32 v246, v117, v246
	v_cvt_pk_bf16_f32 v115, v116, v117
	ds_read_b128 v[90:93], v248 offset:32
	ds_read_b128 v[220:223], v248 offset:4640
	v_exp_f32_e32 v120, v120
	v_exp_f32_e32 v121, v121
	v_add_f32_e32 v246, v118, v246
	v_add_f32_e32 v246, v119, v246
	v_cvt_pk_bf16_f32 v116, v118, v119
	v_mfma_f32_32x32x16_bf16 v[66:81], v[166:169], v[134:137], v[66:81]
	ds_read_b128 v[94:97], v248 offset:64
	ds_read_b128 v[224:227], v248 offset:4672
	v_exp_f32_e32 v122, v122
	v_exp_f32_e32 v123, v123
	v_add_f32_e32 v246, v120, v246
	v_add_f32_e32 v246, v121, v246
	v_cvt_pk_bf16_f32 v117, v120, v121
	v_mfma_f32_32x32x16_bf16 v[34:49], v[182:185], v[134:137], v[34:49]
	ds_read_b128 v[212:215], v248 offset:96
	ds_read_b128 v[242:245], v248 offset:4704
	v_exp_f32_e32 v124, v124
	v_exp_f32_e32 v125, v125
	v_add_f32_e32 v246, v122, v246
	v_add_f32_e32 v246, v123, v246
	v_cvt_pk_bf16_f32 v118, v122, v123
	v_mfma_f32_32x32x16_bf16 v[66:81], v[170:173], v[138:141], v[66:81]
	s_cmp_ge_u32 s11, s16
	s_cbranch_scc1 .Lattn_fx_skipw2
	s_waitcnt vmcnt(2)
	ds_write_b128 v192, v[154:157] offset:55296
	ds_write_b128 v204, v[158:161] offset:64512
.Lattn_fx_skipw2:
	v_exp_f32_e32 v126, v126
	v_exp_f32_e32 v127, v127
	v_add_f32_e32 v246, v124, v246
	v_add_f32_e32 v246, v125, v246
	v_cvt_pk_bf16_f32 v119, v124, v125
	v_mfma_f32_32x32x16_bf16 v[34:49], v[186:189], v[138:141], v[34:49]
	v_exp_f32_e32 v128, v128
	v_exp_f32_e32 v129, v129
	v_add_f32_e32 v246, v126, v246
	v_add_f32_e32 v246, v127, v246
	v_cvt_pk_bf16_f32 v120, v126, v127
	v_mfma_f32_32x32x16_bf16 v[66:81], v[174:177], v[142:145], v[66:81]
	v_exp_f32_e32 v98, v98
	v_exp_f32_e32 v99, v99
	v_add_f32_e32 v246, v128, v246
	v_add_f32_e32 v246, v129, v246
	v_cvt_pk_bf16_f32 v121, v128, v129
	v_mfma_f32_32x32x16_bf16 v[34:49], v[82:85], v[142:145], v[34:49]
	v_exp_f32_e32 v100, v100
	v_exp_f32_e32 v101, v101
	v_add_f32_e32 v247, v98, v99
	v_cvt_pk_bf16_f32 v122, v98, v99
	s_waitcnt lgkmcnt(0)
	s_barrier
	v_mfma_f32_32x32x16_bf16 v[18:33], v[86:89], v[114:117], v[18:33]
	v_mfma_f32_32x32x16_bf16 v[2:17], v[216:219], v[114:117], v[2:17]
	ds_read_b128 v[162:165], v193 offset:55296
	ds_read_b128 v[178:181], v193 offset:59904
	v_exp_f32_e32 v102, v102
	v_exp_f32_e32 v103, v103
	v_add_f32_e32 v247, v100, v247
	v_add_f32_e32 v247, v101, v247
	v_cvt_pk_bf16_f32 v123, v100, v101
	ds_read_b128 v[166:169], v193 offset:55328
	ds_read_b128 v[182:185], v193 offset:59936
	v_exp_f32_e32 v104, v104
	v_exp_f32_e32 v105, v105
	v_add_f32_e32 v247, v102, v247
	v_add_f32_e32 v247, v103, v247
	v_cvt_pk_bf16_f32 v124, v102, v103
	v_mfma_f32_32x32x16_bf16 v[18:33], v[90:93], v[118:121], v[18:33]
	ds_read_b128 v[170:173], v193 offset:55360
	ds_read_b128 v[186:189], v193 offset:59968
	v_exp_f32_e32 v106, v106
	v_exp_f32_e32 v107, v107
	v_add_f32_e32 v247, v104, v247
	v_add_f32_e32 v247, v105, v247
	v_cvt_pk_bf16_f32 v125, v104, v105
	v_mfma_f32_32x32x16_bf16 v[2:17], v[220:223], v[118:121], v[2:17]
	ds_read_b128 v[174:177], v193 offset:55392
	ds_read_b128 v[82:85], v193 offset:60000
	v_exp_f32_e32 v108, v108
	v_exp_f32_e32 v109, v109
	v_add_f32_e32 v247, v106, v247
	v_add_f32_e32 v247, v107, v247
	v_cvt_pk_bf16_f32 v126, v106, v107
	v_mfma_f32_32x32x16_bf16 v[18:33], v[94:97], v[122:125], v[18:33]
	v_exp_f32_e32 v110, v110
	v_exp_f32_e32 v111, v111
	v_add_f32_e32 v247, v108, v247
	v_add_f32_e32 v247, v109, v247
	v_cvt_pk_bf16_f32 v127, v108, v109
	v_mfma_f32_32x32x16_bf16 v[2:17], v[224:227], v[122:125], v[2:17]
	v_exp_f32_e32 v112, v112
	v_exp_f32_e32 v113, v113
	v_add_f32_e32 v247, v110, v247
	v_add_f32_e32 v247, v111, v247
	v_cvt_pk_bf16_f32 v128, v110, v111
	v_cvt_pk_bf16_f32 v129, v112, v113
	v_add_f32_e32 v247, v112, v247
	v_add_f32_e32 v247, v113, v247
	v_mfma_f32_32x32x16_bf16 v[18:33], v[212:215], v[126:129], v[18:33]
	v_mfma_f32_32x32x16_bf16 v[2:17], v[242:245], v[126:129], v[2:17]
	v_add_f32_e32 v210, v210, v246
	v_add_f32_e32 v210, v210, v247
	s_add_i32 s10, s10, 2
	s_cmp_lt_u32 s11, s16
	s_cbranch_scc0 .Lattn_fx_exit0
	s_waitcnt lgkmcnt(0)
	v_mfma_f32_32x32x16_bf16 v[114:129], v[162:165], v[130:133], v[50:65]
	v_mfma_f32_32x32x16_bf16 v[98:113], v[178:181], v[130:133], v[50:65]
	s_add_i32 s11, s10, -1
	s_min_i32 s1, s11, s58
	s_mul_i32 s44, s1, 0xa0000
	s_add_u32 s44, s3, s44
	s_addc_u32 s45, s12, 0
	s_lshl_b32 s46, s1, 7
	s_add_u32 s46, s15, s46
	s_addc_u32 s47, s23, 0
	s_add_i32 s24, s10, -2
	s_cmp_lt_u32 s24, s16
	s_cselect_b64 s[0:1], -1, 0
	global_load_dwordx4 v[154:157], v252, s[44:45] offset:1024
	global_load_dwordx4 v[158:161], v253, s[46:47]
	v_exp_f32_e32 v66, v66
	v_exp_f32_e32 v67, v67
	v_exp_f32_e32 v68, v68
	v_exp_f32_e32 v69, v69
	v_add_f32_e32 v246, v66, v67
	v_cvt_pk_bf16_f32 v66, v66, v67
	ds_read_b128 v[86:89], v248 offset:18432
	ds_read_b128 v[216:219], v248 offset:23040
	v_exp_f32_e32 v70, v70
	v_exp_f32_e32 v71, v71
	v_add_f32_e32 v246, v68, v246
	v_add_f32_e32 v246, v69, v246
	v_cvt_pk_bf16_f32 v67, v68, v69
	ds_read_b128 v[90:93], v248 offset:18464
	ds_read_b128 v[220:223], v248 offset:23072
	v_exp_f32_e32 v72, v72
	v_exp_f32_e32 v73, v73
	v_add_f32_e32 v246, v70, v246
	v_add_f32_e32 v246, v71, v246
	v_cvt_pk_bf16_f32 v68, v70, v71
	v_mfma_f32_32x32x16_bf16 v[114:129], v[166:169], v[134:137], v[114:129]
	ds_read_b128 v[94:97], v248 offset:18496
	ds_read_b128 v[224:227], v248 offset:23104
	v_exp_f32_e32 v74, v74
	v_exp_f32_e32 v75, v75
	v_add_f32_e32 v246, v72, v246
	v_add_f32_e32 v246, v73, v246
	v_cvt_pk_bf16_f32 v69, v72, v73
	v_mfma_f32_32x32x16_bf16 v[98:113], v[182:185], v[134:137], v[98:113]
	ds_read_b128 v[212:215], v248 offset:18528
	ds_read_b128 v[242:245], v248 offset:23136
	v_exp_f32_e32 v76, v76
	v_exp_f32_e32 v77, v77
	v_add_f32_e32 v246, v74, v246
	v_add_f32_e32 v246, v75, v246
	v_cvt_pk_bf16_f32 v70, v74, v75
	v_mfma_f32_32x32x16_bf16 v[114:129], v[170:173], v[138:141], v[114:129]
	s_cmp_ge_u32 s24, s16
	s_cbranch_scc1 .Lattn_fx_skipw3
	s_waitcnt vmcnt(2)
	ds_write_b128 v192, v[146:149] offset:36864
	ds_write_b128 v204, v[150:153] offset:46080
.Lattn_fx_skipw3:
	v_exp_f32_e32 v78, v78
	v_exp_f32_e32 v79, v79
	v_add_f32_e32 v246, v76, v246
	v_add_f32_e32 v246, v77, v246
	v_cvt_pk_bf16_f32 v71, v76, v77
	v_mfma_f32_32x32x16_bf16 v[98:113], v[186:189], v[138:141], v[98:113]
	v_exp_f32_e32 v80, v80
	v_exp_f32_e32 v81, v81
	v_add_f32_e32 v246, v78, v246
	v_add_f32_e32 v246, v79, v246
	v_cvt_pk_bf16_f32 v72, v78, v79
	v_mfma_f32_32x32x16_bf16 v[114:129], v[174:177], v[142:145], v[114:129]
	v_exp_f32_e32 v34, v34
	v_exp_f32_e32 v35, v35
	v_add_f32_e32 v246, v80, v246
	v_add_f32_e32 v246, v81, v246
	v_cvt_pk_bf16_f32 v73, v80, v81
	v_mfma_f32_32x32x16_bf16 v[98:113], v[82:85], v[142:145], v[98:113]
	v_exp_f32_e32 v36, v36
	v_exp_f32_e32 v37, v37
	v_add_f32_e32 v247, v34, v35
	v_cvt_pk_bf16_f32 v74, v34, v35
	s_waitcnt lgkmcnt(0)
	s_barrier
	v_mfma_f32_32x32x16_bf16 v[18:33], v[86:89], v[66:69], v[18:33]
	v_mfma_f32_32x32x16_bf16 v[2:17], v[216:219], v[66:69], v[2:17]
	ds_read_b128 v[162:165], v193 offset:36864
	ds_read_b128 v[178:181], v193 offset:41472
	v_exp_f32_e32 v38, v38
	v_exp_f32_e32 v39, v39
	v_add_f32_e32 v247, v36, v247
	v_add_f32_e32 v247, v37, v247
	v_cvt_pk_bf16_f32 v75, v36, v37
	ds_read_b128 v[166:169], v193 offset:36896
	ds_read_b128 v[182:185], v193 offset:41504
	v_exp_f32_e32 v40, v40
	v_exp_f32_e32 v41, v41
	v_add_f32_e32 v247, v38, v247
	v_add_f32_e32 v247, v39, v247
	v_cvt_pk_bf16_f32 v76, v38, v39
	v_mfma_f32_32x32x16_bf16 v[18:33], v[90:93], v[70:73], v[18:33]
	ds_read_b128 v[170:173], v193 offset:36928
	ds_read_b128 v[186:189], v193 offset:41536
	v_exp_f32_e32 v42, v42
	v_exp_f32_e32 v43, v43
	v_add_f32_e32 v247, v40, v247
	v_add_f32_e32 v247, v41, v247
	v_cvt_pk_bf16_f32 v77, v40, v41
	v_mfma_f32_32x32x16_bf16 v[2:17], v[220:223], v[70:73], v[2:17]
	ds_read_b128 v[174:177], v193 offset:36960
	ds_read_b128 v[82:85], v193 offset:41568
	v_exp_f32_e32 v44, v44
	v_exp_f32_e32 v45, v45
	v_add_f32_e32 v247, v42, v247
	v_add_f32_e32 v247, v43, v247
	v_cvt_pk_bf16_f32 v78, v42, v43
	v_mfma_f32_32x32x16_bf16 v[18:33], v[94:97], v[74:77], v[18:33]
	v_exp_f32_e32 v46, v46
	v_exp_f32_e32 v47, v47
	v_add_f32_e32 v247, v44, v247
	v_add_f32_e32 v247, v45, v247
	v_cvt_pk_bf16_f32 v79, v44, v45
	v_mfma_f32_32x32x16_bf16 v[2:17], v[224:227], v[74:77], v[2:17]
	v_exp_f32_e32 v48, v48
	v_exp_f32_e32 v49, v49
	v_add_f32_e32 v247, v46, v247
	v_add_f32_e32 v247, v47, v247
	v_cvt_pk_bf16_f32 v80, v46, v47
	v_cvt_pk_bf16_f32 v81, v48, v49
	v_add_f32_e32 v247, v48, v247
	v_add_f32_e32 v247, v49, v247
	v_mfma_f32_32x32x16_bf16 v[18:33], v[212:215], v[78:81], v[18:33]
	v_mfma_f32_32x32x16_bf16 v[2:17], v[242:245], v[78:81], v[2:17]
	v_add_f32_e32 v210, v210, v246
	v_add_f32_e32 v210, v210, v247
	s_waitcnt lgkmcnt(0)
	v_mfma_f32_32x32x16_bf16 v[66:81], v[162:165], v[130:133], v[50:65]
	v_mfma_f32_32x32x16_bf16 v[34:49], v[178:181], v[130:133], v[50:65]
	s_min_i32 s24, s10, s58
	s_mul_i32 s44, s24, 0xa0000
	s_add_u32 s44, s3, s44
	s_addc_u32 s45, s12, 0
	s_lshl_b32 s46, s24, 7
	s_add_u32 s46, s15, s46
	s_addc_u32 s47, s23, 0
	global_load_dwordx4 v[146:149], v252, s[44:45] offset:1024
	global_load_dwordx4 v[150:153], v253, s[46:47]
	v_exp_f32_e32 v114, v114
	v_exp_f32_e32 v115, v115
	v_exp_f32_e32 v116, v116
	v_exp_f32_e32 v117, v117
	v_add_f32_e32 v246, v114, v115
	v_cvt_pk_bf16_f32 v114, v114, v115
	ds_read_b128 v[86:89], v248 offset:55296
	ds_read_b128 v[216:219], v248 offset:59904
	v_exp_f32_e32 v118, v118
	v_exp_f32_e32 v119, v119
	v_add_f32_e32 v246, v116, v246
	v_add_f32_e32 v246, v117, v246
	v_cvt_pk_bf16_f32 v115, v116, v117
	ds_read_b128 v[90:93], v248 offset:55328
	ds_read_b128 v[220:223], v248 offset:59936
	v_exp_f32_e32 v120, v120
	v_exp_f32_e32 v121, v121
	v_add_f32_e32 v246, v118, v246
	v_add_f32_e32 v246, v119, v246
	v_cvt_pk_bf16_f32 v116, v118, v119
	v_mfma_f32_32x32x16_bf16 v[66:81], v[166:169], v[134:137], v[66:81]
	ds_read_b128 v[94:97], v248 offset:55360
	ds_read_b128 v[224:227], v248 offset:59968
	v_exp_f32_e32 v122, v122
	v_exp_f32_e32 v123, v123
	v_add_f32_e32 v246, v120, v246
	v_add_f32_e32 v246, v121, v246
	v_cvt_pk_bf16_f32 v117, v120, v121
	v_mfma_f32_32x32x16_bf16 v[34:49], v[182:185], v[134:137], v[34:49]
	ds_read_b128 v[212:215], v248 offset:55392
	ds_read_b128 v[242:245], v248 offset:60000
	v_exp_f32_e32 v124, v124
	v_exp_f32_e32 v125, v125
	v_add_f32_e32 v246, v122, v246
	v_add_f32_e32 v246, v123, v246
	v_cvt_pk_bf16_f32 v118, v122, v123
	v_mfma_f32_32x32x16_bf16 v[66:81], v[170:173], v[138:141], v[66:81]
	s_cmp_ge_u32 s11, s16
	s_cbranch_scc1 .Lattn_fx_skipw4
	s_waitcnt vmcnt(2)
	ds_write_b128 v192, v[154:157]
	ds_write_b128 v204, v[158:161] offset:9216
.Lattn_fx_skipw4:
	v_exp_f32_e32 v126, v126
	v_exp_f32_e32 v127, v127
	v_add_f32_e32 v246, v124, v246
	v_add_f32_e32 v246, v125, v246
	v_cvt_pk_bf16_f32 v119, v124, v125
	v_mfma_f32_32x32x16_bf16 v[34:49], v[186:189], v[138:141], v[34:49]
	v_exp_f32_e32 v128, v128
	v_exp_f32_e32 v129, v129
	v_add_f32_e32 v246, v126, v246
	v_add_f32_e32 v246, v127, v246
	v_cvt_pk_bf16_f32 v120, v126, v127
	v_mfma_f32_32x32x16_bf16 v[66:81], v[174:177], v[142:145], v[66:81]
	v_exp_f32_e32 v98, v98
	v_exp_f32_e32 v99, v99
	v_add_f32_e32 v246, v128, v246
	v_add_f32_e32 v246, v129, v246
	v_cvt_pk_bf16_f32 v121, v128, v129
	v_mfma_f32_32x32x16_bf16 v[34:49], v[82:85], v[142:145], v[34:49]
	v_exp_f32_e32 v100, v100
	v_exp_f32_e32 v101, v101
	v_add_f32_e32 v247, v98, v99
	v_cvt_pk_bf16_f32 v122, v98, v99
	s_waitcnt lgkmcnt(0)
	s_barrier
	v_mfma_f32_32x32x16_bf16 v[18:33], v[86:89], v[114:117], v[18:33]
	v_mfma_f32_32x32x16_bf16 v[2:17], v[216:219], v[114:117], v[2:17]
	ds_read_b128 v[162:165], v193
	ds_read_b128 v[178:181], v193 offset:4608
	v_exp_f32_e32 v102, v102
	v_exp_f32_e32 v103, v103
	v_add_f32_e32 v247, v100, v247
	v_add_f32_e32 v247, v101, v247
	v_cvt_pk_bf16_f32 v123, v100, v101
	ds_read_b128 v[166:169], v193 offset:32
	ds_read_b128 v[182:185], v193 offset:4640
	v_exp_f32_e32 v104, v104
	v_exp_f32_e32 v105, v105
	v_add_f32_e32 v247, v102, v247
	v_add_f32_e32 v247, v103, v247
	v_cvt_pk_bf16_f32 v124, v102, v103
	v_mfma_f32_32x32x16_bf16 v[18:33], v[90:93], v[118:121], v[18:33]
	ds_read_b128 v[170:173], v193 offset:64
	ds_read_b128 v[186:189], v193 offset:4672
	v_exp_f32_e32 v106, v106
	v_exp_f32_e32 v107, v107
	v_add_f32_e32 v247, v104, v247
	v_add_f32_e32 v247, v105, v247
	v_cvt_pk_bf16_f32 v125, v104, v105
	v_mfma_f32_32x32x16_bf16 v[2:17], v[220:223], v[118:121], v[2:17]
	ds_read_b128 v[174:177], v193 offset:96
	ds_read_b128 v[82:85], v193 offset:4704
	v_exp_f32_e32 v108, v108
	v_exp_f32_e32 v109, v109
	v_add_f32_e32 v247, v106, v247
	v_add_f32_e32 v247, v107, v247
	v_cvt_pk_bf16_f32 v126, v106, v107
	v_mfma_f32_32x32x16_bf16 v[18:33], v[94:97], v[122:125], v[18:33]
	v_exp_f32_e32 v110, v110
	v_exp_f32_e32 v111, v111
	v_add_f32_e32 v247, v108, v247
	v_add_f32_e32 v247, v109, v247
	v_cvt_pk_bf16_f32 v127, v108, v109
	v_mfma_f32_32x32x16_bf16 v[2:17], v[224:227], v[122:125], v[2:17]
	v_exp_f32_e32 v112, v112
	v_exp_f32_e32 v113, v113
	v_add_f32_e32 v247, v110, v247
	v_add_f32_e32 v247, v111, v247
	v_cvt_pk_bf16_f32 v128, v110, v111
	v_cvt_pk_bf16_f32 v129, v112, v113
	v_add_f32_e32 v247, v112, v247
	v_add_f32_e32 v247, v113, v247
	v_mfma_f32_32x32x16_bf16 v[18:33], v[212:215], v[126:129], v[18:33]
	v_mfma_f32_32x32x16_bf16 v[2:17], v[242:245], v[126:129], v[2:17]
	v_add_f32_e32 v210, v210, v246
	v_add_f32_e32 v210, v210, v247
	s_add_i32 s10, s10, 2
	s_cmp_lt_u32 s11, s16
	s_cbranch_scc0 .Lattn_fx_exit1
	s_branch .Lattn_fx_top
